# v64 plus w_in epilogue row-stat atomics as global atomics without the vmcnt(0) drain in front of each
# baseline (speedup 1.0000x reference)
.LBB0_206:
	v_lshl_add_u32 v146, s56, 8, v150
	s_cmp_eq_u32 s78, 4
	s_mov_b64 s[18:19], -1
	v_readlane_b32 s86, v255, 44
	s_mov_b64 s[84:85], s[88:89]
	s_mov_b32 s83, s94
	v_readlane_b32 s87, v255, 45
	s_cbranch_scc1 .LBB0_240
	v_lshl_or_b32 v148, s78, 8, v154
	s_cmp_lt_i32 s78, 4
	v_mov_b64_e32 v[156:157], s[22:23]
	v_ashrrev_i32_e32 v149, 31, v148
	s_cselect_b64 s[56:57], -1, 0
	s_ashr_i32 s18, s78, 1
	v_mad_i64_i32 v[156:157], s[36:37], v146, s40, v[156:157]
	s_ashr_i32 s19, s18, 31
	v_lshl_add_u64 v[156:157], v[148:149], 1, v[156:157]
	v_cvt_pk_bf16_f32 v168, v60, v61
	v_cvt_pk_bf16_f32 v169, v62, v63
	v_cvt_pk_bf16_f32 v170, v56, v57
	v_cvt_pk_bf16_f32 v171, v58, v59
	s_and_b64 vcc, exec, s[56:57]
	global_store_dwordx4 v[156:157], v[168:171], off
	s_nop 1
	v_cvt_pk_bf16_f32 v168, v126, v127
	v_cvt_pk_bf16_f32 v169, v128, v129
	v_cvt_pk_bf16_f32 v170, v122, v123
	v_cvt_pk_bf16_f32 v171, v124, v125
	global_store_dwordx4 v[156:157], v[168:171], off offset:256
	s_cbranch_vccz .LBB0_211
	v_mul_f32_e32 v96, v61, v61
	v_mul_f32_e32 v147, v63, v63
	v_mul_f32_e32 v127, v127, v127
	v_fmac_f32_e32 v96, v60, v60
	v_fmac_f32_e32 v147, v62, v62
	v_fmac_f32_e32 v127, v126, v126
	v_mul_f32_e32 v126, v129, v129
	v_add_f32_e32 v96, v96, v147
	v_mul_f32_e32 v147, v57, v57
	v_fmac_f32_e32 v126, v128, v128
	v_mul_f32_e32 v123, v123, v123
	v_fmac_f32_e32 v147, v56, v56
	v_add_f32_e32 v126, v127, v126
	v_fmac_f32_e32 v123, v122, v122
	v_add_f32_e32 v96, v96, v147
	v_mul_f32_e32 v147, v59, v59
	v_add_f32_e32 v122, v126, v123
	v_mul_f32_e32 v123, v125, v125
	v_fmac_f32_e32 v147, v58, v58
	v_fmac_f32_e32 v123, v124, v124
	v_add_f32_e32 v96, v147, v96
	v_add_f32_e32 v122, v123, v122
	v_add_f32_e32 v96, v96, v122
	ds_bpermute_b32 v122, v152, v96
	s_waitcnt lgkmcnt(0)
	v_add_f32_e32 v96, v96, v122
	ds_bpermute_b32 v122, v153, v96
	s_and_saveexec_b64 s[36:37], s[0:1]
	s_cbranch_execz .LBB0_210
	v_ashrrev_i32_e32 v147, 31, v146
	v_lshl_add_u64 v[124:125], v[146:147], 3, s[24:25]
	v_lshl_add_u64 v[124:125], s[18:19], 2, v[124:125]
	s_waitcnt lgkmcnt(0)
	v_add_f32_e32 v96, v96, v122
	global_atomic_add_f32 v[124:125], v96, off

.LBB0_211:
	s_waitcnt lgkmcnt(0)
	v_or_b32_e32 v122, 16, v146
	v_mov_b64_e32 v[124:125], s[22:23]
	v_mad_i64_i32 v[124:125], s[36:37], v122, s40, v[124:125]
	v_cndmask_b32_e64 v96, 0, 1, s[56:57]
	v_lshl_add_u64 v[128:129], v[148:149], 1, v[124:125]
	v_cvt_pk_bf16_f32 v124, v52, v53
	v_cvt_pk_bf16_f32 v125, v54, v55
	v_cvt_pk_bf16_f32 v126, v48, v49
	v_cvt_pk_bf16_f32 v127, v50, v51
	v_cmp_ne_u32_e64 s[36:37], 1, v96
	s_andn2_b64 vcc, exec, s[56:57]
	global_store_dwordx4 v[128:129], v[124:127], off
	s_nop 1
	v_cvt_pk_bf16_f32 v124, v118, v119
	v_cvt_pk_bf16_f32 v125, v120, v121
	v_cvt_pk_bf16_f32 v126, v114, v115
	v_cvt_pk_bf16_f32 v127, v116, v117
	global_store_dwordx4 v[128:129], v[124:127], off offset:256
	s_cbranch_vccnz .LBB0_215
	v_mul_f32_e32 v96, v53, v53
	v_mul_f32_e32 v123, v55, v55
	v_mul_f32_e32 v119, v119, v119
	v_fmac_f32_e32 v96, v52, v52
	v_fmac_f32_e32 v123, v54, v54
	v_fmac_f32_e32 v119, v118, v118
	v_mul_f32_e32 v118, v121, v121
	v_add_f32_e32 v96, v96, v123
	v_mul_f32_e32 v123, v49, v49
	v_fmac_f32_e32 v118, v120, v120
	v_mul_f32_e32 v115, v115, v115
	v_fmac_f32_e32 v123, v48, v48
	v_add_f32_e32 v118, v119, v118
	v_fmac_f32_e32 v115, v114, v114
	v_add_f32_e32 v96, v96, v123
	v_mul_f32_e32 v123, v51, v51
	v_add_f32_e32 v114, v118, v115
	v_mul_f32_e32 v115, v117, v117
	v_fmac_f32_e32 v123, v50, v50
	v_fmac_f32_e32 v115, v116, v116
	v_add_f32_e32 v96, v123, v96
	v_add_f32_e32 v114, v115, v114
	v_add_f32_e32 v96, v96, v114
	ds_bpermute_b32 v114, v152, v96
	s_waitcnt lgkmcnt(0)
	v_add_f32_e32 v96, v96, v114
	ds_bpermute_b32 v114, v153, v96
	s_and_saveexec_b64 s[56:57], s[0:1]
	s_cbranch_execz .LBB0_214
	v_ashrrev_i32_e32 v123, 31, v122
	v_lshl_add_u64 v[116:117], v[122:123], 3, s[24:25]
	v_lshl_add_u64 v[116:117], s[18:19], 2, v[116:117]
	s_waitcnt lgkmcnt(0)
	v_add_f32_e32 v96, v96, v114
	global_atomic_add_f32 v[116:117], v96, off

.LBB0_215:
	s_waitcnt lgkmcnt(0)
	v_or_b32_e32 v114, 32, v146
	v_mov_b64_e32 v[116:117], s[22:23]
	v_mad_i64_i32 v[116:117], s[56:57], v114, s40, v[116:117]
	v_lshl_add_u64 v[120:121], v[148:149], 1, v[116:117]
	v_cvt_pk_bf16_f32 v116, v44, v45
	v_cvt_pk_bf16_f32 v117, v46, v47
	v_cvt_pk_bf16_f32 v118, v40, v41
	v_cvt_pk_bf16_f32 v119, v42, v43
	s_and_b64 vcc, exec, s[36:37]
	global_store_dwordx4 v[120:121], v[116:119], off
	s_nop 1
	v_cvt_pk_bf16_f32 v116, v110, v111
	v_cvt_pk_bf16_f32 v117, v112, v113
	v_cvt_pk_bf16_f32 v118, v106, v107
	v_cvt_pk_bf16_f32 v119, v108, v109
	global_store_dwordx4 v[120:121], v[116:119], off offset:256
	s_cbranch_vccnz .LBB0_219
	v_mul_f32_e32 v96, v45, v45
	v_mul_f32_e32 v115, v47, v47
	v_mul_f32_e32 v111, v111, v111
	v_fmac_f32_e32 v96, v44, v44
	v_fmac_f32_e32 v115, v46, v46
	v_fmac_f32_e32 v111, v110, v110
	v_mul_f32_e32 v110, v113, v113
	v_add_f32_e32 v96, v96, v115
	v_mul_f32_e32 v115, v41, v41
	v_fmac_f32_e32 v110, v112, v112
	v_mul_f32_e32 v107, v107, v107
	v_fmac_f32_e32 v115, v40, v40
	v_add_f32_e32 v110, v111, v110
	v_fmac_f32_e32 v107, v106, v106
	v_add_f32_e32 v96, v96, v115
	v_mul_f32_e32 v115, v43, v43
	v_add_f32_e32 v106, v110, v107
	v_mul_f32_e32 v107, v109, v109
	v_fmac_f32_e32 v115, v42, v42
	v_fmac_f32_e32 v107, v108, v108
	v_add_f32_e32 v96, v115, v96
	v_add_f32_e32 v106, v107, v106
	v_add_f32_e32 v96, v96, v106
	ds_bpermute_b32 v106, v152, v96
	s_waitcnt lgkmcnt(0)
	v_add_f32_e32 v96, v96, v106
	ds_bpermute_b32 v106, v153, v96
	s_and_saveexec_b64 s[56:57], s[0:1]
	s_cbranch_execz .LBB0_218
	v_ashrrev_i32_e32 v115, 31, v114
	v_lshl_add_u64 v[108:109], v[114:115], 3, s[24:25]
	v_lshl_add_u64 v[108:109], s[18:19], 2, v[108:109]
	s_waitcnt lgkmcnt(0)
	v_add_f32_e32 v96, v96, v106
	global_atomic_add_f32 v[108:109], v96, off

.LBB0_219:
	s_waitcnt lgkmcnt(0)
	v_or_b32_e32 v106, 48, v146
	v_mov_b64_e32 v[108:109], s[22:23]
	v_mad_i64_i32 v[108:109], s[56:57], v106, s40, v[108:109]
	v_lshl_add_u64 v[112:113], v[148:149], 1, v[108:109]
	v_cvt_pk_bf16_f32 v108, v36, v37
	v_cvt_pk_bf16_f32 v109, v38, v39
	v_cvt_pk_bf16_f32 v110, v32, v33
	v_cvt_pk_bf16_f32 v111, v34, v35
	s_and_b64 vcc, exec, s[36:37]
	global_store_dwordx4 v[112:113], v[108:111], off
	s_nop 1
	v_cvt_pk_bf16_f32 v108, v102, v103
	v_cvt_pk_bf16_f32 v109, v104, v105
	v_cvt_pk_bf16_f32 v110, v98, v99
	v_cvt_pk_bf16_f32 v111, v100, v101
	global_store_dwordx4 v[112:113], v[108:111], off offset:256
	s_cbranch_vccnz .LBB0_223
	v_mul_f32_e32 v96, v37, v37
	v_mul_f32_e32 v107, v39, v39
	v_mul_f32_e32 v103, v103, v103
	v_fmac_f32_e32 v96, v36, v36
	v_fmac_f32_e32 v107, v38, v38
	v_fmac_f32_e32 v103, v102, v102
	v_mul_f32_e32 v102, v105, v105
	v_add_f32_e32 v96, v96, v107
	v_mul_f32_e32 v107, v33, v33
	v_fmac_f32_e32 v102, v104, v104
	v_mul_f32_e32 v99, v99, v99
	v_fmac_f32_e32 v107, v32, v32
	v_add_f32_e32 v102, v103, v102
	v_fmac_f32_e32 v99, v98, v98
	v_add_f32_e32 v96, v96, v107
	v_mul_f32_e32 v107, v35, v35
	v_add_f32_e32 v98, v102, v99
	v_mul_f32_e32 v99, v101, v101
	v_fmac_f32_e32 v107, v34, v34
	v_fmac_f32_e32 v99, v100, v100
	v_add_f32_e32 v96, v107, v96
	v_add_f32_e32 v98, v99, v98
	v_add_f32_e32 v96, v96, v98
	ds_bpermute_b32 v98, v152, v96
	s_waitcnt lgkmcnt(0)
	v_add_f32_e32 v96, v96, v98
	ds_bpermute_b32 v98, v153, v96
	s_and_saveexec_b64 s[56:57], s[0:1]
	s_cbranch_execz .LBB0_222
	v_ashrrev_i32_e32 v107, 31, v106
	v_lshl_add_u64 v[100:101], v[106:107], 3, s[24:25]
	v_lshl_add_u64 v[100:101], s[18:19], 2, v[100:101]
	s_waitcnt lgkmcnt(0)
	v_add_f32_e32 v96, v96, v98
	global_atomic_add_f32 v[100:101], v96, off

.LBB0_223:
	s_waitcnt lgkmcnt(0)
	v_add_u32_e32 v98, 0x80, v146
	v_mov_b64_e32 v[100:101], s[22:23]
	v_mad_i64_i32 v[100:101], s[56:57], v98, s40, v[100:101]
	v_lshl_add_u64 v[104:105], v[148:149], 1, v[100:101]
	v_cvt_pk_bf16_f32 v100, v28, v29
	v_cvt_pk_bf16_f32 v101, v30, v31
	v_cvt_pk_bf16_f32 v102, v24, v25
	v_cvt_pk_bf16_f32 v103, v26, v27
	s_and_b64 vcc, exec, s[36:37]
	global_store_dwordx4 v[104:105], v[100:103], off
	s_nop 1
	v_cvt_pk_bf16_f32 v100, v92, v93
	v_cvt_pk_bf16_f32 v101, v94, v95
	v_cvt_pk_bf16_f32 v102, v88, v89
	v_cvt_pk_bf16_f32 v103, v90, v91
	global_store_dwordx4 v[104:105], v[100:103], off offset:256
	s_cbranch_vccnz .LBB0_227
	v_mul_f32_e32 v96, v29, v29
	v_mul_f32_e32 v99, v31, v31
	v_mul_f32_e32 v93, v93, v93
	v_fmac_f32_e32 v96, v28, v28
	v_fmac_f32_e32 v99, v30, v30
	v_fmac_f32_e32 v93, v92, v92
	v_mul_f32_e32 v92, v95, v95
	v_add_f32_e32 v96, v96, v99
	v_mul_f32_e32 v99, v25, v25
	v_fmac_f32_e32 v92, v94, v94
	v_mul_f32_e32 v89, v89, v89
	v_fmac_f32_e32 v99, v24, v24
	v_add_f32_e32 v92, v93, v92
	v_fmac_f32_e32 v89, v88, v88
	v_add_f32_e32 v96, v96, v99
	v_mul_f32_e32 v99, v27, v27
	v_add_f32_e32 v88, v92, v89
	v_mul_f32_e32 v89, v91, v91
	v_fmac_f32_e32 v99, v26, v26
	v_fmac_f32_e32 v89, v90, v90
	v_add_f32_e32 v96, v99, v96
	v_add_f32_e32 v88, v89, v88
	v_add_f32_e32 v88, v96, v88
	ds_bpermute_b32 v89, v152, v88
	s_waitcnt lgkmcnt(0)
	v_add_f32_e32 v88, v88, v89
	ds_bpermute_b32 v89, v153, v88
	s_and_saveexec_b64 s[56:57], s[0:1]
	s_cbranch_execz .LBB0_226
	v_ashrrev_i32_e32 v99, 31, v98
	v_lshl_add_u64 v[90:91], v[98:99], 3, s[24:25]
	v_lshl_add_u64 v[90:91], s[18:19], 2, v[90:91]
	s_waitcnt lgkmcnt(0)
	v_add_f32_e32 v88, v88, v89
	global_atomic_add_f32 v[90:91], v88, off

.LBB0_227:
	v_add_u32_e32 v88, 0x90, v146
	v_mov_b64_e32 v[90:91], s[22:23]
	v_mad_i64_i32 v[90:91], s[56:57], v88, s40, v[90:91]
	v_lshl_add_u64 v[94:95], v[148:149], 1, v[90:91]
	v_cvt_pk_bf16_f32 v90, v20, v21
	v_cvt_pk_bf16_f32 v91, v22, v23
	v_cvt_pk_bf16_f32 v92, v16, v17
	v_cvt_pk_bf16_f32 v93, v18, v19
	s_and_b64 vcc, exec, s[36:37]
	global_store_dwordx4 v[94:95], v[90:93], off
	s_nop 1
	v_cvt_pk_bf16_f32 v90, v84, v85
	v_cvt_pk_bf16_f32 v91, v86, v87
	v_cvt_pk_bf16_f32 v92, v80, v81
	v_cvt_pk_bf16_f32 v93, v82, v83
	global_store_dwordx4 v[94:95], v[90:93], off offset:256
	s_cbranch_vccnz .LBB0_231
	s_waitcnt lgkmcnt(0)
	v_mul_f32_e32 v89, v21, v21
	v_mul_f32_e32 v90, v23, v23
	v_mul_f32_e32 v85, v85, v85
	v_fmac_f32_e32 v89, v20, v20
	v_fmac_f32_e32 v90, v22, v22
	v_fmac_f32_e32 v85, v84, v84
	v_mul_f32_e32 v84, v87, v87
	v_add_f32_e32 v89, v89, v90
	v_mul_f32_e32 v90, v17, v17
	v_fmac_f32_e32 v84, v86, v86
	v_mul_f32_e32 v81, v81, v81
	v_fmac_f32_e32 v90, v16, v16
	v_add_f32_e32 v84, v85, v84
	v_fmac_f32_e32 v81, v80, v80
	v_add_f32_e32 v89, v89, v90
	v_mul_f32_e32 v90, v19, v19
	v_add_f32_e32 v80, v84, v81
	v_mul_f32_e32 v81, v83, v83
	v_fmac_f32_e32 v90, v18, v18
	v_fmac_f32_e32 v81, v82, v82
	v_add_f32_e32 v89, v90, v89
	v_add_f32_e32 v80, v81, v80
	v_add_f32_e32 v80, v89, v80
	ds_bpermute_b32 v81, v152, v80
	s_waitcnt lgkmcnt(0)
	v_add_f32_e32 v80, v80, v81
	ds_bpermute_b32 v81, v153, v80
	s_and_saveexec_b64 s[56:57], s[0:1]
	s_cbranch_execz .LBB0_230
	v_ashrrev_i32_e32 v89, 31, v88
	v_lshl_add_u64 v[82:83], v[88:89], 3, s[24:25]
	v_lshl_add_u64 v[82:83], s[18:19], 2, v[82:83]
	s_waitcnt lgkmcnt(0)
	v_add_f32_e32 v80, v80, v81
	global_atomic_add_f32 v[82:83], v80, off

.LBB0_231:
	v_add_u32_e32 v80, 0xa0, v146
	v_mov_b64_e32 v[82:83], s[22:23]
	v_mad_i64_i32 v[82:83], s[56:57], v80, s40, v[82:83]
	v_lshl_add_u64 v[86:87], v[148:149], 1, v[82:83]
	v_cvt_pk_bf16_f32 v82, v12, v13
	v_cvt_pk_bf16_f32 v83, v14, v15
	v_cvt_pk_bf16_f32 v84, v8, v9
	v_cvt_pk_bf16_f32 v85, v10, v11
	s_and_b64 vcc, exec, s[36:37]
	global_store_dwordx4 v[86:87], v[82:85], off
	s_nop 1
	v_cvt_pk_bf16_f32 v82, v76, v77
	v_cvt_pk_bf16_f32 v83, v78, v79
	v_cvt_pk_bf16_f32 v84, v72, v73
	v_cvt_pk_bf16_f32 v85, v74, v75
	global_store_dwordx4 v[86:87], v[82:85], off offset:256
	s_cbranch_vccnz .LBB0_235
	s_waitcnt lgkmcnt(0)
	v_mul_f32_e32 v81, v13, v13
	v_mul_f32_e32 v82, v15, v15
	v_mul_f32_e32 v77, v77, v77
	v_fmac_f32_e32 v81, v12, v12
	v_fmac_f32_e32 v82, v14, v14
	v_fmac_f32_e32 v77, v76, v76
	v_mul_f32_e32 v76, v79, v79
	v_add_f32_e32 v81, v81, v82
	v_mul_f32_e32 v82, v9, v9
	v_fmac_f32_e32 v76, v78, v78
	v_mul_f32_e32 v73, v73, v73
	v_fmac_f32_e32 v82, v8, v8
	v_add_f32_e32 v76, v77, v76
	v_fmac_f32_e32 v73, v72, v72
	v_add_f32_e32 v81, v81, v82
	v_mul_f32_e32 v82, v11, v11
	v_add_f32_e32 v72, v76, v73
	v_mul_f32_e32 v73, v75, v75
	v_fmac_f32_e32 v82, v10, v10
	v_fmac_f32_e32 v73, v74, v74
	v_add_f32_e32 v81, v82, v81
	v_add_f32_e32 v72, v73, v72
	v_add_f32_e32 v72, v81, v72
	ds_bpermute_b32 v73, v152, v72
	s_waitcnt lgkmcnt(0)
	v_add_f32_e32 v72, v72, v73
	ds_bpermute_b32 v73, v153, v72
	s_and_saveexec_b64 s[56:57], s[0:1]
	s_cbranch_execz .LBB0_234
	v_ashrrev_i32_e32 v81, 31, v80
	v_lshl_add_u64 v[74:75], v[80:81], 3, s[24:25]
	v_lshl_add_u64 v[74:75], s[18:19], 2, v[74:75]
	s_waitcnt lgkmcnt(0)
	v_add_f32_e32 v72, v72, v73
	global_atomic_add_f32 v[74:75], v72, off

.LBB0_235:
	v_add_u32_e32 v72, 0xb0, v146
	v_mov_b64_e32 v[74:75], s[22:23]
	v_mad_i64_i32 v[74:75], s[56:57], v72, s40, v[74:75]
	v_lshl_add_u64 v[78:79], v[148:149], 1, v[74:75]
	v_cvt_pk_bf16_f32 v74, v4, v5
	v_cvt_pk_bf16_f32 v75, v6, v7
	v_cvt_pk_bf16_f32 v76, v0, v1
	v_cvt_pk_bf16_f32 v77, v2, v3
	s_and_b64 vcc, exec, s[36:37]
	global_store_dwordx4 v[78:79], v[74:77], off
	s_nop 1
	v_cvt_pk_bf16_f32 v74, v68, v69
	v_cvt_pk_bf16_f32 v75, v70, v71
	v_cvt_pk_bf16_f32 v76, v64, v65
	v_cvt_pk_bf16_f32 v77, v66, v67
	global_store_dwordx4 v[78:79], v[74:77], off offset:256
	s_cbranch_vccnz .LBB0_239
	s_waitcnt lgkmcnt(0)
	v_mul_f32_e32 v73, v5, v5
	v_mul_f32_e32 v74, v7, v7
	v_mul_f32_e32 v69, v69, v69
	v_fmac_f32_e32 v73, v4, v4
	v_fmac_f32_e32 v74, v6, v6
	v_fmac_f32_e32 v69, v68, v68
	v_mul_f32_e32 v68, v71, v71
	v_add_f32_e32 v73, v73, v74
	v_mul_f32_e32 v74, v1, v1
	v_fmac_f32_e32 v68, v70, v70
	v_mul_f32_e32 v65, v65, v65
	v_fmac_f32_e32 v74, v0, v0
	v_add_f32_e32 v68, v69, v68
	v_fmac_f32_e32 v65, v64, v64
	v_add_f32_e32 v73, v73, v74
	v_mul_f32_e32 v74, v3, v3
	v_add_f32_e32 v64, v68, v65
	v_mul_f32_e32 v65, v67, v67
	v_fmac_f32_e32 v74, v2, v2
	v_fmac_f32_e32 v65, v66, v66
	v_add_f32_e32 v73, v74, v73
	v_add_f32_e32 v64, v65, v64
	v_add_f32_e32 v64, v73, v64
	ds_bpermute_b32 v65, v152, v64
	s_waitcnt lgkmcnt(0)
	v_add_f32_e32 v64, v64, v65
	ds_bpermute_b32 v65, v153, v64
	s_and_saveexec_b64 s[36:37], s[0:1]
	s_cbranch_execz .LBB0_238
	v_ashrrev_i32_e32 v73, 31, v72
	v_lshl_add_u64 v[66:67], v[72:73], 3, s[24:25]
	v_lshl_add_u64 v[66:67], s[18:19], 2, v[66:67]
	s_waitcnt lgkmcnt(0)
	v_add_f32_e32 v64, v64, v65
	global_atomic_add_f32 v[66:67], v64, off
